# rms1 row loop: next row's loads issued before the current row's reduce/scale/store (one row of loads always in flight)
# baseline (speedup 1.0000x reference)
; template <bool OUTF32>
; __device__ __forceinline__ void rmsnorm_rows(const float* src, const float* w, u16* dstb, float* dstf, const int wvi) {
;   const int tid = tidx(wvi);
;   const int lane = tid & 63, wv = __builtin_amdgcn_readfirstlane(tid >> 6);
;   src = lptr(src); w = lptr(w); dstb = lptr(dstb); dstf = lptr(dstf);
;   float4 gw[8];
; #pragma unroll
;   for (int i = 0; i < 8; ++i) gw[i] = *(const float4*)(w + i * 256 + lane * 4);
;   for (int row = blockIdx.x * 8 + wv; row < PT; row += gridDim.x * 8) {
;     const float* s = src + (size_t)row * DM;
;     float4 v[8];
;     float ss = 0.f;
; #pragma unroll
;     for (int i = 0; i < 8; ++i) {
;       v[i] = ldnt4(s + i * 256 + lane * 4);
;       ss += v[i].x * v[i].x + v[i].y * v[i].y + v[i].z * v[i].z + v[i].w * v[i].w;
;     }
;     ss = wave_sum(ss, lane);
.LBB0_118:
	s_lshl_b32 s4, s0, 25
	s_mov_b32 s2, s4
	v_writelane_b32 v243, s2, 41
	v_mbcnt_lo_u32_b32 v0, -1, 0
	v_mbcnt_hi_u32_b32 v0, -1, v0
	s_nop 0
	v_add_u32_e32 v1, s48, v0
	v_writelane_b32 v243, s3, 42
	s_add_i32 s2, s4, 0xfe000000
	s_cmp_eq_u32 s0, 0
	v_writelane_b32 v243, s0, 43
	s_cselect_b64 s[0:1], -1, 0
	v_writelane_b32 v243, s0, 44
	s_mov_b32 s3, s19
	s_nop 0
	v_writelane_b32 v243, s1, 45
	s_and_b64 s[0:1], s[0:1], exec
	s_cselect_b32 s0, 0, 8
	v_writelane_b32 v243, s0, 46
	v_readfirstlane_b32 s0, v1
	s_cselect_b32 s2, 0, s2
	s_ashr_i32 s0, s0, 6
	v_readlane_b32 s1, v246, 6
	s_add_i32 s0, s0, s1
	s_cmpk_gt_i32 s0, 0x3fff
	v_writelane_b32 v243, s2, 47
	s_nop 1
	v_writelane_b32 v243, s3, 48
	s_cbranch_scc1 .LBB0_121
	v_lshlrev_b32_e32 v34, 2, v0
	v_and_b32_e32 v35, 0xfc, v34
	v_readlane_b32 s2, v244, 40
	v_lshlrev_b32_e32 v144, 2, v35
	v_readlane_b32 s3, v244, 41
	s_movk_i32 s6, 0x1000
	s_nop 3
	global_load_dwordx4 v[0:3], v144, s[2:3]
	global_load_dwordx4 v[4:7], v144, s[2:3] offset:1024
	global_load_dwordx4 v[8:11], v144, s[2:3] offset:2048
	global_load_dwordx4 v[12:15], v144, s[2:3] offset:3072
	v_lshl_add_u64 v[16:17], s[2:3], 0, v[144:145]
	v_add_co_u32_e32 v28, vcc, s6, v16
	v_readlane_b32 s2, v246, 0
	s_nop 0
	v_addc_co_u32_e32 v29, vcc, 0, v17, vcc
	global_load_dwordx4 v[16:19], v[28:29], off
	global_load_dwordx4 v[20:23], v[28:29], off offset:1024
	global_load_dwordx4 v[24:27], v[28:29], off offset:2048
	s_nop 0
	global_load_dwordx4 v[28:31], v[28:29], off offset:3072
	v_readlane_b32 s1, v243, 46
	v_readlane_b32 s3, v246, 1
	s_add_u32 s2, s2, s1
	s_addc_u32 s3, s3, 0
	s_load_dwordx2 s[2:3], s[2:3], 0x0
	v_readlane_b32 s4, v243, 47
	v_readlane_b32 s5, v243, 48
	s_lshl_b64 s[4:5], s[4:5], 2
	s_movk_i32 s1, 0x80
	s_waitcnt lgkmcnt(0)
	s_add_u32 s2, s2, s4
	s_addc_u32 s3, s3, s5
	v_lshl_add_u64 v[32:33], s[2:3], 0, v[144:145]
	v_lshlrev_b32_e32 v144, 1, v35
	v_bitop3_b32 v36, v34, s1, v199 bitop3:0x6c
	v_bitop3_b32 v37, v34, 64, v199 bitop3:0x6c
	v_bitop3_b32 v38, v34, 32, v199 bitop3:0x6c
	v_bitop3_b32 v39, v34, 16, v199 bitop3:0x6c
	v_bitop3_b32 v40, v34, 8, v199 bitop3:0x6c
	v_bitop3_b32 v41, v34, 4, v199 bitop3:0x6c
	v_lshl_add_u64 v[34:35], s[52:53], 0, v[144:145]
	s_ashr_i32 s1, s0, 31
	s_lshl_b64 s[2:3], s[0:1], 13
	v_lshl_add_u64 v[100:101], v[32:33], 0, s[2:3]
	v_add_co_u32_e32 v102, vcc, s6, v100
	s_nop 1
	v_addc_co_u32_e32 v103, vcc, 0, v101, vcc
	global_load_dwordx4 v[42:45], v[100:101], off nt
	global_load_dwordx4 v[46:49], v[100:101], off offset:1024 nt
	global_load_dwordx4 v[50:53], v[100:101], off offset:2048 nt
	global_load_dwordx4 v[54:57], v[100:101], off offset:3072 nt
	global_load_dwordx4 v[58:61], v[102:103], off nt
	global_load_dwordx4 v[62:65], v[102:103], off offset:1024 nt
	global_load_dwordx4 v[66:69], v[102:103], off offset:2048 nt
	global_load_dwordx4 v[70:73], v[102:103], off offset:3072 nt
	s_waitcnt vmcnt(0)
; template <bool OUTF32>
; __device__ __forceinline__ void rmsnorm_rows(const float* src, const float* w, u16* dstb, float* dstf, const int wvi) {
;     ...
;   for (int row = blockIdx.x * 8 + wv; row < PT; row += gridDim.x * 8) {
;     const float* s = src + (size_t)row * DM;
;     float4 v[8];
;     float ss = 0.f;
; #pragma unroll
;     for (int i = 0; i < 8; ++i) {
;       v[i] = ldnt4(s + i * 256 + lane * 4);
;       ss += v[i].x * v[i].x + v[i].y * v[i].y + v[i].z * v[i].z + v[i].w * v[i].w;
;     }
;     ss = wave_sum(ss, lane);
;     const float rstd = rsqrtf(ss * (1.f / DM) + EPS);
; #pragma unroll
;     for (int i = 0; i < 8; ++i) {
;       const int c = i * 256 + lane * 4;
;       const float4 g = gw[i];
;       float o0 = v[i].x * rstd * g.x, o1 = v[i].y * rstd * g.y, o2 = v[i].z * rstd * g.z, o3 = v[i].w * rstd * g.w;
;       if (OUTF32) {
;         *(float4*)(dstf + (size_t)row * DM + c) = make_float4(o0, o1, o2, o3);
;       } else {
;         uint2 o; o.x = pk2(o0, o1); o.y = pk2(o2, o3);
;         *(uint2*)(dstb + (size_t)row * DM + c) = o;
;       }
;     }
;   }
.LBB0_120:
	s_add_i32 s8, s0, s31
	s_cmpk_lt_i32 s8, 0x4000
	s_cselect_b32 s8, s8, s0
	s_ashr_i32 s9, s8, 31
	s_lshl_b64 s[8:9], s[8:9], 13
	v_lshl_add_u64 v[100:101], v[32:33], 0, s[8:9]
	v_add_co_u32_e32 v102, vcc, s6, v100
	s_nop 1
	v_addc_co_u32_e32 v103, vcc, 0, v101, vcc
	global_load_dwordx4 v[210:213], v[100:101], off nt
	global_load_dwordx4 v[214:217], v[100:101], off offset:1024 nt
	global_load_dwordx4 v[218:221], v[100:101], off offset:2048 nt
	global_load_dwordx4 v[222:225], v[100:101], off offset:3072 nt
	global_load_dwordx4 v[226:229], v[102:103], off nt
	global_load_dwordx4 v[230:233], v[102:103], off offset:1024 nt
	global_load_dwordx4 v[234:237], v[102:103], off offset:2048 nt
	global_load_dwordx4 v[238:241], v[102:103], off offset:3072 nt
	s_ashr_i32 s1, s0, 31
	s_lshl_b64 s[2:3], s[0:1], 12
	s_add_i32 s0, s0, s31
	s_cmpk_lt_i32 s0, 0x4000
	v_mul_f32_e32 v90, v43, v43
	v_mul_f32_e32 v91, v47, v47
	v_mul_f32_e32 v92, v51, v51
	v_fmac_f32_e32 v90, v42, v42
	v_fmac_f32_e32 v91, v46, v46
	v_mul_f32_e32 v93, v55, v55
	v_fmac_f32_e32 v92, v50, v50
	v_mov_b32_e32 v76, v59
	v_mov_b32_e32 v77, v63
	v_mov_b32_e32 v80, v67
	v_mov_b32_e32 v81, v71
	v_fmac_f32_e32 v90, v44, v44
	v_fmac_f32_e32 v91, v48, v48
	v_fmac_f32_e32 v93, v54, v54
	v_mov_b32_e32 v74, v58
	v_mov_b32_e32 v75, v62
	v_mov_b32_e32 v78, v66
	v_mov_b32_e32 v79, v70
	v_fmac_f32_e32 v92, v52, v52
	v_pk_mul_f32 v[76:77], v[76:77], v[76:77]
	v_pk_mul_f32 v[80:81], v[80:81], v[80:81]
	v_fmac_f32_e32 v90, v45, v45
	v_fmac_f32_e32 v91, v49, v49
	v_mov_b32_e32 v82, v60
	v_mov_b32_e32 v83, v64
	v_fmac_f32_e32 v93, v56, v56
	v_fmac_f32_e32 v92, v53, v53
	v_pk_fma_f32 v[74:75], v[74:75], v[74:75], v[76:77]
	v_pk_fma_f32 v[76:77], v[78:79], v[78:79], v[80:81]
	v_add_f32_e32 v78, v90, v91
	v_mov_b32_e32 v86, v61
	v_mov_b32_e32 v87, v65
	v_fmac_f32_e32 v93, v57, v57
	v_pk_fma_f32 v[74:75], v[82:83], v[82:83], v[74:75]
	v_add_f32_e32 v78, v78, v92
	v_mov_b32_e32 v84, v68
	v_mov_b32_e32 v85, v72
	v_pk_fma_f32 v[74:75], v[86:87], v[86:87], v[74:75]
	v_add_f32_e32 v78, v78, v93
	v_mov_b32_e32 v88, v69
	v_mov_b32_e32 v89, v73
	v_pk_fma_f32 v[76:77], v[84:85], v[84:85], v[76:77]
	v_add_f32_e32 v74, v78, v74
	v_pk_fma_f32 v[76:77], v[88:89], v[88:89], v[76:77]
	v_add_f32_e32 v74, v74, v75
	v_add_f32_e32 v74, v74, v76
	v_add_f32_e32 v74, v74, v77
	ds_bpermute_b32 v75, v36, v74
	s_waitcnt lgkmcnt(0)
	v_add_f32_e32 v74, v74, v75
	ds_bpermute_b32 v75, v37, v74
	s_waitcnt lgkmcnt(0)
	v_add_f32_e32 v74, v74, v75
	ds_bpermute_b32 v75, v38, v74
	s_waitcnt lgkmcnt(0)
	v_add_f32_e32 v74, v74, v75
	ds_bpermute_b32 v75, v39, v74
	s_waitcnt lgkmcnt(0)
	v_add_f32_e32 v74, v74, v75
	ds_bpermute_b32 v75, v40, v74
	s_waitcnt lgkmcnt(0)
	v_add_f32_e32 v74, v74, v75
	ds_bpermute_b32 v75, v41, v74
	s_waitcnt lgkmcnt(0)
	v_add_f32_e32 v74, v74, v75
	v_fmamk_f32 v74, v74, 0x3a000000, v165
	v_mul_f32_e32 v75, 0x4b800000, v74
	v_cmp_gt_f32_e32 vcc, s88, v74
	s_nop 1
	v_cndmask_b32_e32 v74, v74, v75, vcc
	v_rsq_f32_e32 v76, v74
	v_lshl_add_u64 v[74:75], v[34:35], 0, s[2:3]
	v_mul_f32_e32 v77, 0x45800000, v76
	v_cndmask_b32_e32 v76, v76, v77, vcc
	v_pk_mul_f32 v[42:43], v[42:43], v[76:77] op_sel_hi:[1,0]
	v_pk_mul_f32 v[44:45], v[44:45], v[76:77] op_sel_hi:[1,0]
	v_pk_mul_f32 v[46:47], v[46:47], v[76:77] op_sel_hi:[1,0]
	v_pk_mul_f32 v[48:49], v[48:49], v[76:77] op_sel_hi:[1,0]
	v_pk_mul_f32 v[50:51], v[50:51], v[76:77] op_sel_hi:[1,0]
	v_pk_mul_f32 v[52:53], v[52:53], v[76:77] op_sel_hi:[1,0]
	v_pk_mul_f32 v[54:55], v[54:55], v[76:77] op_sel_hi:[1,0]
	v_pk_mul_f32 v[56:57], v[56:57], v[76:77] op_sel_hi:[1,0]
	v_pk_mul_f32 v[58:59], v[58:59], v[76:77] op_sel_hi:[1,0]
	v_pk_mul_f32 v[60:61], v[60:61], v[76:77] op_sel_hi:[1,0]
	v_pk_mul_f32 v[62:63], v[62:63], v[76:77] op_sel_hi:[1,0]
	v_pk_mul_f32 v[64:65], v[64:65], v[76:77] op_sel_hi:[1,0]
	v_pk_mul_f32 v[66:67], v[66:67], v[76:77] op_sel_hi:[1,0]
	v_pk_mul_f32 v[68:69], v[68:69], v[76:77] op_sel_hi:[1,0]
	v_pk_mul_f32 v[70:71], v[70:71], v[76:77] op_sel_hi:[1,0]
	v_pk_mul_f32 v[72:73], v[72:73], v[76:77] op_sel_hi:[1,0]
	v_pk_mul_f32 v[42:43], v[0:1], v[42:43]
	v_pk_mul_f32 v[44:45], v[2:3], v[44:45]
	v_pk_mul_f32 v[46:47], v[4:5], v[46:47]
	v_pk_mul_f32 v[48:49], v[6:7], v[48:49]
	v_pk_mul_f32 v[50:51], v[8:9], v[50:51]
	v_pk_mul_f32 v[52:53], v[10:11], v[52:53]
	v_pk_mul_f32 v[54:55], v[12:13], v[54:55]
	v_pk_mul_f32 v[56:57], v[14:15], v[56:57]
	v_pk_mul_f32 v[58:59], v[16:17], v[58:59]
	v_pk_mul_f32 v[60:61], v[18:19], v[60:61]
	v_pk_mul_f32 v[62:63], v[20:21], v[62:63]
	v_pk_mul_f32 v[64:65], v[22:23], v[64:65]
	v_pk_mul_f32 v[66:67], v[24:25], v[66:67]
	v_pk_mul_f32 v[68:69], v[26:27], v[68:69]
	v_pk_mul_f32 v[70:71], v[28:29], v[70:71]
	v_pk_mul_f32 v[72:73], v[30:31], v[72:73]
	v_cvt_pk_bf16_f32 v42, v42, v43
	v_cvt_pk_bf16_f32 v43, v44, v45
	v_cvt_pk_bf16_f32 v44, v46, v47
	v_cvt_pk_bf16_f32 v45, v48, v49
	v_cvt_pk_bf16_f32 v46, v50, v51
	v_cvt_pk_bf16_f32 v47, v52, v53
	v_cvt_pk_bf16_f32 v48, v54, v55
	v_cvt_pk_bf16_f32 v49, v56, v57
	v_cvt_pk_bf16_f32 v50, v58, v59
	v_cvt_pk_bf16_f32 v51, v60, v61
	v_cvt_pk_bf16_f32 v52, v62, v63
	v_cvt_pk_bf16_f32 v53, v64, v65
	v_cvt_pk_bf16_f32 v54, v66, v67
	v_cvt_pk_bf16_f32 v55, v68, v69
	v_cvt_pk_bf16_f32 v56, v70, v71
	v_cvt_pk_bf16_f32 v57, v72, v73
	global_store_dwordx2 v[74:75], v[42:43], off
	global_store_dwordx2 v[74:75], v[44:45], off offset:512
	global_store_dwordx2 v[74:75], v[46:47], off offset:1024
	global_store_dwordx2 v[74:75], v[48:49], off offset:1536
	global_store_dwordx2 v[74:75], v[50:51], off offset:2048
	global_store_dwordx2 v[74:75], v[52:53], off offset:2560
	global_store_dwordx2 v[74:75], v[54:55], off offset:3072
	global_store_dwordx2 v[74:75], v[56:57], off offset:3584
	s_waitcnt vmcnt(8)
	v_mov_b32_e32 v42, v210
	v_mov_b32_e32 v43, v211
	v_mov_b32_e32 v44, v212
	v_mov_b32_e32 v45, v213
	v_mov_b32_e32 v46, v214
	v_mov_b32_e32 v47, v215
	v_mov_b32_e32 v48, v216
	v_mov_b32_e32 v49, v217
	v_mov_b32_e32 v50, v218
	v_mov_b32_e32 v51, v219
	v_mov_b32_e32 v52, v220
	v_mov_b32_e32 v53, v221
	v_mov_b32_e32 v54, v222
	v_mov_b32_e32 v55, v223
	v_mov_b32_e32 v56, v224
	v_mov_b32_e32 v57, v225
	v_mov_b32_e32 v58, v226
	v_mov_b32_e32 v59, v227
	v_mov_b32_e32 v60, v228
	v_mov_b32_e32 v61, v229
	v_mov_b32_e32 v62, v230
	v_mov_b32_e32 v63, v231
	v_mov_b32_e32 v64, v232
	v_mov_b32_e32 v65, v233
	v_mov_b32_e32 v66, v234
	v_mov_b32_e32 v67, v235
	v_mov_b32_e32 v68, v236
	v_mov_b32_e32 v69, v237
	v_mov_b32_e32 v70, v238
	v_mov_b32_e32 v71, v239
	v_mov_b32_e32 v72, v240
	v_mov_b32_e32 v73, v241
	s_cbranch_scc1 .LBB0_120
